# RG-LRU: unmasked fast-path depthwise conv for interior tiles (LDS weight reads batched two taps ahead, no exec-mask blocks); boundary tiles keep the original path
# speedup vs baseline: 1.0067x; 1.0008x over previous
.LBB0_355:
	s_cmp_gt_u32 s94, 1
	s_cselect_b64 s[12:13], -1, 0
	s_lshl_b32 s14, s94, 7
	s_and_b32 s14, s14, 0x1f00
	s_addk_i32 s14, 0xff00
	s_cmp_lt_u32 s94, 2
	s_cselect_b32 s14, 0, s14
	s_cselect_b32 s54, 0x100, s58
	s_lshl_b32 s15, s94, 4
	s_add_i32 s14, s14, s85
	s_and_b32 s15, s15, 16
	s_or_b32 s14, s14, s15
	v_or_b32_e32 v0, s14, v236
	ds_read_b128 v[128:131], v241 offset:38400
	ds_read_b128 v[124:127], v241 offset:38416
	v_xad_u32 v122, v0, -1, s54
	v_cndmask_b32_e64 v246, v122, v0, s[44:45]
	v_add_u32_e32 v123, -2, v246
	s_add_i32 s15, s54, -4
	v_cmp_ge_u32_e32 vcc, s15, v123
	s_nop 0
	s_cmp_eq_u64 vcc, exec
	s_cbranch_scc1 .Lrg_fast
	s_or_b32 s14, s54, 2
	v_cmp_lt_i32_e32 vcc, 1, v246
	v_cmp_gt_i32_e64 s[52:53], s14, v246
	s_and_b64 s[14:15], vcc, s[52:53]
	s_and_saveexec_b64 s[16:17], s[14:15]
	s_cbranch_execz .LBB0_357
	ds_read_b128 v[132:135], v241 offset:36864
	ds_read_b128 v[136:139], v241 offset:36880
	s_waitcnt vmcnt(11)
	v_lshlrev_b32_e32 v122, 16, v2
	v_and_b32_e32 v123, 0xffff0000, v2
	s_waitcnt lgkmcnt(1)
	v_pk_fma_f32 v[128:129], v[132:133], v[122:123], v[128:129]
	v_lshlrev_b32_e32 v122, 16, v3
	v_and_b32_e32 v123, 0xffff0000, v3
	v_pk_fma_f32 v[130:131], v[134:135], v[122:123], v[130:131]
	v_lshlrev_b32_e32 v122, 16, v4
	v_and_b32_e32 v123, 0xffff0000, v4
	s_waitcnt lgkmcnt(0)
	v_pk_fma_f32 v[124:125], v[136:137], v[122:123], v[124:125]
	v_lshlrev_b32_e32 v122, 16, v5
	v_and_b32_e32 v123, 0xffff0000, v5
	v_pk_fma_f32 v[126:127], v[138:139], v[122:123], v[126:127]

.Lrg_fast:
	ds_read_b128 v[132:135], v241 offset:36864
	ds_read_b128 v[136:139], v241 offset:36880
	ds_read_b128 v[140:143], v241 offset:37248
	ds_read_b128 v[144:147], v241 offset:37264
	s_waitcnt vmcnt(11) lgkmcnt(2)
	v_lshlrev_b32_e32 v122, 16, v2
	v_and_b32_e32 v123, 0xffff0000, v2
	v_pk_fma_f32 v[128:129], v[132:133], v[122:123], v[128:129]
	v_lshlrev_b32_e32 v122, 16, v3
	v_and_b32_e32 v123, 0xffff0000, v3
	v_pk_fma_f32 v[130:131], v[134:135], v[122:123], v[130:131]
	v_lshlrev_b32_e32 v122, 16, v4
	v_and_b32_e32 v123, 0xffff0000, v4
	v_pk_fma_f32 v[124:125], v[136:137], v[122:123], v[124:125]
	v_lshlrev_b32_e32 v122, 16, v5
	v_and_b32_e32 v123, 0xffff0000, v5
	v_pk_fma_f32 v[126:127], v[138:139], v[122:123], v[126:127]
	ds_read_b128 v[132:135], v241 offset:37632
	ds_read_b128 v[136:139], v241 offset:37648
	s_waitcnt vmcnt(8) lgkmcnt(2)
	v_lshlrev_b32_e32 v122, 16, v14
	v_and_b32_e32 v123, 0xffff0000, v14
	v_pk_fma_f32 v[128:129], v[140:141], v[122:123], v[128:129]
	v_lshlrev_b32_e32 v122, 16, v15
	v_and_b32_e32 v123, 0xffff0000, v15
	v_pk_fma_f32 v[130:131], v[142:143], v[122:123], v[130:131]
	v_lshlrev_b32_e32 v122, 16, v16
	v_and_b32_e32 v123, 0xffff0000, v16
	v_pk_fma_f32 v[124:125], v[144:145], v[122:123], v[124:125]
	v_lshlrev_b32_e32 v122, 16, v17
	v_and_b32_e32 v123, 0xffff0000, v17
	v_pk_fma_f32 v[126:127], v[146:147], v[122:123], v[126:127]
	ds_read_b128 v[140:143], v241 offset:38016
	ds_read_b128 v[144:147], v241 offset:38032
	s_waitcnt vmcnt(5) lgkmcnt(2)
	v_lshlrev_b32_e32 v122, 16, v26
	v_and_b32_e32 v123, 0xffff0000, v26
	v_pk_fma_f32 v[128:129], v[132:133], v[122:123], v[128:129]
	v_lshlrev_b32_e32 v122, 16, v27
	v_and_b32_e32 v123, 0xffff0000, v27
	v_pk_fma_f32 v[130:131], v[134:135], v[122:123], v[130:131]
	v_lshlrev_b32_e32 v122, 16, v28
	v_and_b32_e32 v123, 0xffff0000, v28
	v_pk_fma_f32 v[124:125], v[136:137], v[122:123], v[124:125]
	v_lshlrev_b32_e32 v122, 16, v29
	v_and_b32_e32 v123, 0xffff0000, v29
	v_pk_fma_f32 v[126:127], v[138:139], v[122:123], v[126:127]
	s_waitcnt vmcnt(2) lgkmcnt(0)
	v_lshlrev_b32_e32 v122, 16, v38
	v_and_b32_e32 v123, 0xffff0000, v38
	v_pk_fma_f32 v[128:129], v[140:141], v[122:123], v[128:129]
	v_lshlrev_b32_e32 v122, 16, v39
	v_and_b32_e32 v123, 0xffff0000, v39
	v_pk_fma_f32 v[130:131], v[142:143], v[122:123], v[130:131]
	v_lshlrev_b32_e32 v122, 16, v40
	v_and_b32_e32 v123, 0xffff0000, v40
	v_pk_fma_f32 v[124:125], v[144:145], v[122:123], v[124:125]
	v_lshlrev_b32_e32 v122, 16, v41
	v_and_b32_e32 v123, 0xffff0000, v41
	v_pk_fma_f32 v[126:127], v[146:147], v[122:123], v[126:127]
	ds_write_b128 v242, v[128:131] offset:40960
	ds_write_b128 v242, v[124:127] offset:40976
	v_cvt_pk_bf16_f32 v122, v128, v129
	v_cvt_pk_bf16_f32 v123, v130, v131
	v_cvt_pk_bf16_f32 v124, v124, v125
	v_cvt_pk_bf16_f32 v125, v126, v127
	ds_read_b128 v[132:135], v241 offset:38528
	ds_read_b128 v[136:139], v241 offset:38544
	ds_read_b128 v[140:143], v241 offset:36992
	ds_read_b128 v[144:147], v241 offset:37008
	ds_read_b128 v[170:173], v241 offset:37376
	ds_read_b128 v[248:251], v241 offset:37392
	s_waitcnt vmcnt(10) lgkmcnt(2)
	v_lshlrev_b32_e32 v130, 16, v6
	v_and_b32_e32 v131, 0xffff0000, v6
	v_pk_fma_f32 v[132:133], v[140:141], v[130:131], v[132:133]
	v_lshlrev_b32_e32 v130, 16, v7
	v_and_b32_e32 v131, 0xffff0000, v7
	v_pk_fma_f32 v[134:135], v[142:143], v[130:131], v[134:135]
	v_lshlrev_b32_e32 v130, 16, v8
	v_and_b32_e32 v131, 0xffff0000, v8
	v_pk_fma_f32 v[136:137], v[144:145], v[130:131], v[136:137]
	v_lshlrev_b32_e32 v130, 16, v9
	v_and_b32_e32 v131, 0xffff0000, v9
	v_pk_fma_f32 v[138:139], v[146:147], v[130:131], v[138:139]
	ds_read_b128 v[140:143], v241 offset:37760
	ds_read_b128 v[144:147], v241 offset:37776
	s_waitcnt vmcnt(7) lgkmcnt(2)
	v_lshlrev_b32_e32 v130, 16, v18
	v_and_b32_e32 v131, 0xffff0000, v18
	v_pk_fma_f32 v[132:133], v[170:171], v[130:131], v[132:133]
	v_lshlrev_b32_e32 v130, 16, v19
	v_and_b32_e32 v131, 0xffff0000, v19
	v_pk_fma_f32 v[134:135], v[172:173], v[130:131], v[134:135]
	v_lshlrev_b32_e32 v130, 16, v20
	v_and_b32_e32 v131, 0xffff0000, v20
	v_pk_fma_f32 v[136:137], v[248:249], v[130:131], v[136:137]
	v_lshlrev_b32_e32 v130, 16, v21
	v_and_b32_e32 v131, 0xffff0000, v21
	v_pk_fma_f32 v[138:139], v[250:251], v[130:131], v[138:139]
	ds_read_b128 v[170:173], v241 offset:38144
	ds_read_b128 v[248:251], v241 offset:38160
	s_waitcnt vmcnt(4) lgkmcnt(2)
	v_lshlrev_b32_e32 v130, 16, v30
	v_and_b32_e32 v131, 0xffff0000, v30
	v_pk_fma_f32 v[132:133], v[140:141], v[130:131], v[132:133]
	v_lshlrev_b32_e32 v130, 16, v31
	v_and_b32_e32 v131, 0xffff0000, v31
	v_pk_fma_f32 v[134:135], v[142:143], v[130:131], v[134:135]
	v_lshlrev_b32_e32 v130, 16, v32
	v_and_b32_e32 v131, 0xffff0000, v32
	v_pk_fma_f32 v[136:137], v[144:145], v[130:131], v[136:137]
	v_lshlrev_b32_e32 v130, 16, v33
	v_and_b32_e32 v131, 0xffff0000, v33
	v_pk_fma_f32 v[138:139], v[146:147], v[130:131], v[138:139]
	s_waitcnt vmcnt(1) lgkmcnt(0)
	v_lshlrev_b32_e32 v130, 16, v42
	v_and_b32_e32 v131, 0xffff0000, v42
	v_pk_fma_f32 v[132:133], v[170:171], v[130:131], v[132:133]
	v_lshlrev_b32_e32 v130, 16, v43
	v_and_b32_e32 v131, 0xffff0000, v43
	v_pk_fma_f32 v[134:135], v[172:173], v[130:131], v[134:135]
	v_lshlrev_b32_e32 v130, 16, v44
	v_and_b32_e32 v131, 0xffff0000, v44
	v_pk_fma_f32 v[136:137], v[248:249], v[130:131], v[136:137]
	v_lshlrev_b32_e32 v130, 16, v45
	v_and_b32_e32 v131, 0xffff0000, v45
	v_pk_fma_f32 v[138:139], v[250:251], v[130:131], v[138:139]
	ds_write_b128 v242, v[132:135] offset:41088
	ds_write_b128 v242, v[136:139] offset:41104
	v_cvt_pk_bf16_f32 v126, v132, v133
	v_cvt_pk_bf16_f32 v127, v134, v135
	v_cvt_pk_bf16_f32 v128, v136, v137
	v_cvt_pk_bf16_f32 v129, v138, v139
	ds_read_b128 v[132:135], v241 offset:38656
	ds_read_b128 v[136:139], v241 offset:38672
	ds_read_b128 v[140:143], v241 offset:37120
	ds_read_b128 v[144:147], v241 offset:37136
	ds_read_b128 v[170:173], v241 offset:37504
	ds_read_b128 v[248:251], v241 offset:37520
	s_waitcnt vmcnt(9) lgkmcnt(2)
	v_lshlrev_b32_e32 v130, 16, v10
	v_and_b32_e32 v131, 0xffff0000, v10
	v_pk_fma_f32 v[132:133], v[140:141], v[130:131], v[132:133]
	v_lshlrev_b32_e32 v130, 16, v11
	v_and_b32_e32 v131, 0xffff0000, v11
	v_pk_fma_f32 v[134:135], v[142:143], v[130:131], v[134:135]
	v_lshlrev_b32_e32 v130, 16, v12
	v_and_b32_e32 v131, 0xffff0000, v12
	v_pk_fma_f32 v[136:137], v[144:145], v[130:131], v[136:137]
	v_lshlrev_b32_e32 v130, 16, v13
	v_and_b32_e32 v131, 0xffff0000, v13
	v_pk_fma_f32 v[138:139], v[146:147], v[130:131], v[138:139]
	ds_read_b128 v[140:143], v241 offset:37888
	ds_read_b128 v[144:147], v241 offset:37904
	s_waitcnt vmcnt(6) lgkmcnt(2)
	v_lshlrev_b32_e32 v130, 16, v22
	v_and_b32_e32 v131, 0xffff0000, v22
	v_pk_fma_f32 v[132:133], v[170:171], v[130:131], v[132:133]
	v_lshlrev_b32_e32 v130, 16, v23
	v_and_b32_e32 v131, 0xffff0000, v23
	v_pk_fma_f32 v[134:135], v[172:173], v[130:131], v[134:135]
	v_lshlrev_b32_e32 v130, 16, v24
	v_and_b32_e32 v131, 0xffff0000, v24
	v_pk_fma_f32 v[136:137], v[248:249], v[130:131], v[136:137]
	v_lshlrev_b32_e32 v130, 16, v25
	v_and_b32_e32 v131, 0xffff0000, v25
	v_pk_fma_f32 v[138:139], v[250:251], v[130:131], v[138:139]
	ds_read_b128 v[170:173], v241 offset:38272
	ds_read_b128 v[248:251], v241 offset:38288
	s_waitcnt vmcnt(3) lgkmcnt(2)
	v_lshlrev_b32_e32 v130, 16, v34
	v_and_b32_e32 v131, 0xffff0000, v34
	v_pk_fma_f32 v[132:133], v[140:141], v[130:131], v[132:133]
	v_lshlrev_b32_e32 v130, 16, v35
	v_and_b32_e32 v131, 0xffff0000, v35
	v_pk_fma_f32 v[134:135], v[142:143], v[130:131], v[134:135]
	v_lshlrev_b32_e32 v130, 16, v36
	v_and_b32_e32 v131, 0xffff0000, v36
	v_pk_fma_f32 v[136:137], v[144:145], v[130:131], v[136:137]
	v_lshlrev_b32_e32 v130, 16, v37
	v_and_b32_e32 v131, 0xffff0000, v37
	v_pk_fma_f32 v[138:139], v[146:147], v[130:131], v[138:139]
	s_waitcnt vmcnt(0) lgkmcnt(0)
	v_lshlrev_b32_e32 v130, 16, v46
	v_and_b32_e32 v131, 0xffff0000, v46
	v_pk_fma_f32 v[132:133], v[170:171], v[130:131], v[132:133]
	v_lshlrev_b32_e32 v130, 16, v47
	v_and_b32_e32 v131, 0xffff0000, v47
	v_pk_fma_f32 v[134:135], v[172:173], v[130:131], v[134:135]
	v_lshlrev_b32_e32 v130, 16, v48
	v_and_b32_e32 v131, 0xffff0000, v48
	v_pk_fma_f32 v[136:137], v[248:249], v[130:131], v[136:137]
	v_lshlrev_b32_e32 v130, 16, v49
	v_and_b32_e32 v131, 0xffff0000, v49
	v_pk_fma_f32 v[138:139], v[250:251], v[130:131], v[138:139]
	s_and_saveexec_b64 s[52:53], s[50:51]
	ds_write_b128 v242, v[132:135] offset:41216
	ds_write_b128 v242, v[136:139] offset:41232
	s_mov_b64 exec, s[52:53]
	v_cvt_pk_bf16_f32 v146, v132, v133
	v_cvt_pk_bf16_f32 v147, v134, v135
	v_cvt_pk_bf16_f32 v148, v136, v137
	v_cvt_pk_bf16_f32 v149, v138, v139
	v_cndmask_b32_e64 v146, 0, v146, s[50:51]
	v_cndmask_b32_e64 v147, 0, v147, s[50:51]
	v_cndmask_b32_e64 v148, 0, v148, s[50:51]
	v_cndmask_b32_e64 v149, 0, v149, s[50:51]
	s_branch .LBB0_381
